# NSA selected loop: sink the 64 per-block accumulator copies (v_mov) to the loop exit in the 4 nsa_wg instances
# speedup vs baseline: 1.0086x; 1.0053x over previous
.LBB0_2477:
	s_lshl_b32 s21, s20, 5
	v_or_b32_e32 v151, s21, v226
	v_mad_u32_u24 v151, v151, s52, v148
	ds_read_b128 v[152:155], v151
	ds_read_b128 v[156:159], v151 offset:64
	ds_read_b128 v[160:163], v151 offset:2304
	ds_read_b128 v[164:167], v151 offset:2368
	v_lshl_add_u32 v151, s20, 6, v149
	ds_read_b128 v[168:171], v151 offset:9216
	ds_read_b128 v[172:175], v151 offset:11520
	ds_read_b128 v[176:179], v151 offset:13824
	ds_read_b128 v[182:185], v151 offset:16128
	v_add_u32_e32 v151, s21, v150
	v_sub_u32_e32 v180, v227, v151
	v_cmp_gt_u32_e32 vcc, 2.0, v180
	v_cvt_f32_i32_e32 v180, v180
	v_xad_u32 v186, v151, -1, v227
	v_cvt_f32_i32_e32 v187, v186
	s_and_b64 vcc, s[16:17], vcc
	v_cndmask_b32_e32 v180, v235, v180, vcc
	v_cmp_gt_u32_e32 vcc, 2.0, v186
	v_or_b32_e32 v186, 2, v151
	s_and_b64 vcc, s[16:17], vcc
	v_sub_u32_e32 v186, v227, v186
	v_cndmask_b32_e32 v236, v235, v187, vcc
	v_cmp_gt_u32_e32 vcc, 2.0, v186
	v_cvt_f32_i32_e32 v186, v186
	v_or_b32_e32 v187, 3, v151
	v_sub_u32_e32 v187, v227, v187
	v_cvt_f32_i32_e32 v188, v187
	s_and_b64 vcc, s[16:17], vcc
	v_cndmask_b32_e32 v237, v235, v186, vcc
	v_cmp_gt_u32_e32 vcc, 2.0, v187
	v_or_b32_e32 v186, 4, v151
	s_and_b64 vcc, s[16:17], vcc
	v_sub_u32_e32 v186, v227, v186
	v_cndmask_b32_e32 v238, v235, v188, vcc
	v_cmp_gt_u32_e32 vcc, 2.0, v186
	v_cvt_f32_i32_e32 v186, v186
	v_or_b32_e32 v187, 5, v151
	v_sub_u32_e32 v187, v227, v187
	v_cvt_f32_i32_e32 v188, v187
	s_and_b64 vcc, s[16:17], vcc
	v_cndmask_b32_e32 v239, v235, v186, vcc
	v_cmp_gt_u32_e32 vcc, 2.0, v187
	v_or_b32_e32 v186, 6, v151
	s_and_b64 vcc, s[16:17], vcc
	v_sub_u32_e32 v186, v227, v186
	v_cndmask_b32_e32 v240, v235, v188, vcc
	v_cmp_gt_u32_e32 vcc, 2.0, v186
	v_cvt_f32_i32_e32 v186, v186
	v_or_b32_e32 v151, 7, v151
	v_sub_u32_e32 v151, v227, v151
	v_cvt_f32_i32_e32 v187, v151
	s_and_b64 vcc, s[16:17], vcc
	v_cndmask_b32_e32 v241, v235, v186, vcc
	v_cmp_gt_u32_e32 vcc, 2.0, v151
	s_and_b64 vcc, s[16:17], vcc
	s_nop 0
	v_cndmask_b32_e32 v151, v235, v187, vcc
	s_setprio 1
	s_waitcnt lgkmcnt(7)
	v_mfma_f32_16x16x32_bf16 v[186:189], v[152:155], v[2:5], 0
	v_mfma_f32_16x16x32_bf16 v[194:197], v[152:155], v[10:13], 0
	v_mfma_f32_16x16x32_bf16 v[202:205], v[152:155], v[18:21], 0
	v_mfma_f32_16x16x32_bf16 v[152:155], v[152:155], v[26:29], 0
	s_waitcnt lgkmcnt(6)
	v_mfma_f32_16x16x32_bf16 v[186:189], v[156:159], v[6:9], v[186:189]
	s_waitcnt lgkmcnt(5)
	v_mfma_f32_16x16x32_bf16 v[190:193], v[160:163], v[2:5], 0
	v_mfma_f32_16x16x32_bf16 v[194:197], v[156:159], v[14:17], v[194:197]
	v_mfma_f32_16x16x32_bf16 v[198:201], v[160:163], v[10:13], 0
	v_mfma_f32_16x16x32_bf16 v[202:205], v[156:159], v[22:25], v[202:205]
	v_mfma_f32_16x16x32_bf16 v[206:209], v[160:163], v[18:21], 0
	v_mfma_f32_16x16x32_bf16 v[152:155], v[156:159], v[30:33], v[152:155]
	v_mfma_f32_16x16x32_bf16 v[156:159], v[160:163], v[26:29], 0
	s_waitcnt lgkmcnt(4)
	v_mfma_f32_16x16x32_bf16 v[190:193], v[164:167], v[6:9], v[190:193]
	v_mfma_f32_16x16x32_bf16 v[198:201], v[164:167], v[14:17], v[198:201]
	v_mfma_f32_16x16x32_bf16 v[206:209], v[164:167], v[22:25], v[206:209]
	v_mfma_f32_16x16x32_bf16 v[156:159], v[164:167], v[30:33], v[156:159]
	s_setprio 0
	v_fma_f32 v160, -v215, v180, v186
	v_fma_f32 v164, -v216, v180, v194
	v_exp_f32_e32 v165, v160
	v_fma_f32 v160, -v215, v236, v187
	v_exp_f32_e32 v164, v164
	v_fma_f32 v166, -v216, v236, v195
	v_exp_f32_e32 v167, v160
	v_fma_f32 v160, -v215, v237, v188
	v_exp_f32_e32 v166, v166
	v_fma_f32 v186, -v216, v237, v196
	v_exp_f32_e32 v187, v160
	v_fma_f32 v160, -v215, v238, v189
	v_exp_f32_e32 v186, v186
	v_fma_f32 v188, -v216, v238, v197
	v_exp_f32_e32 v189, v160
	v_fma_f32 v160, -v215, v239, v190
	v_exp_f32_e32 v188, v188
	v_fma_f32 v190, -v216, v239, v198
	v_exp_f32_e32 v211, v160
	v_fma_f32 v160, -v215, v240, v191
	v_exp_f32_e32 v210, v190
	v_fma_f32 v190, -v216, v240, v199
	v_pk_add_f32 v[194:195], v[164:165], 0 op_sel_hi:[1,0]
	v_exp_f32_e32 v191, v160
	v_fma_f32 v160, -v215, v241, v192
	v_exp_f32_e32 v190, v190
	v_fma_f32 v192, -v216, v241, v200
	v_pk_add_f32 v[194:195], v[166:167], v[194:195]
	v_exp_f32_e32 v213, v160
	v_fma_f32 v160, -v215, v151, v193
	v_exp_f32_e32 v212, v192
	v_fma_f32 v192, -v216, v151, v201
	v_pk_add_f32 v[194:195], v[186:187], v[194:195]
	v_exp_f32_e32 v193, v160
	v_exp_f32_e32 v192, v192
	v_pk_add_f32 v[194:195], v[188:189], v[194:195]
	v_fma_f32 v152, -v218, v180, v152
	v_pk_add_f32 v[194:195], v[210:211], v[194:195]
	v_cvt_pk_bf16_f32 v164, v164, v166
	v_pk_add_f32 v[194:195], v[190:191], v[194:195]
	v_cvt_pk_bf16_f32 v166, v210, v190
	v_pk_add_f32 v[194:195], v[212:213], v[194:195]
	v_exp_f32_e32 v190, v152
	v_fma_f32 v152, -v218, v236, v153
	v_cvt_pk_bf16_f32 v160, v165, v167
	v_pk_add_f32 v[194:195], v[192:193], v[194:195]
	v_cvt_pk_bf16_f32 v165, v186, v188
	v_cvt_pk_bf16_f32 v167, v212, v192
	v_fma_f32 v186, -v217, v180, v202
	v_exp_f32_e32 v192, v152
	v_fma_f32 v152, -v218, v237, v154
	v_cvt_pk_bf16_f32 v162, v211, v191
	v_pk_add_f32 v[122:123], v[122:123], v[194:195]
	v_exp_f32_e32 v191, v186
	v_fma_f32 v186, -v217, v236, v203
	v_exp_f32_e32 v194, v152
	v_fma_f32 v152, -v218, v238, v155
	v_cvt_pk_bf16_f32 v163, v213, v193
	v_exp_f32_e32 v193, v186
	v_fma_f32 v186, -v217, v237, v204
	v_exp_f32_e32 v196, v152
	v_fma_f32 v152, -v218, v239, v156
	v_exp_f32_e32 v195, v186
	v_fma_f32 v186, -v217, v238, v205
	v_exp_f32_e32 v198, v152
	v_fma_f32 v152, -v218, v240, v157
	v_exp_f32_e32 v197, v186
	v_fma_f32 v186, -v217, v239, v206
	v_exp_f32_e32 v200, v152
	v_fma_f32 v152, -v218, v241, v158
	v_exp_f32_e32 v199, v186
	v_fma_f32 v186, -v217, v240, v207
	v_exp_f32_e32 v202, v152
	v_pk_add_f32 v[152:153], v[190:191], 0 op_sel_hi:[1,0]
	v_exp_f32_e32 v201, v186
	v_fma_f32 v186, -v217, v241, v208
	v_pk_add_f32 v[152:153], v[192:193], v[152:153]
	v_exp_f32_e32 v203, v186
	v_fma_f32 v186, -v217, v151, v209
	v_fma_f32 v151, -v218, v151, v159
	v_pk_add_f32 v[152:153], v[194:195], v[152:153]
	v_exp_f32_e32 v205, v186
	v_exp_f32_e32 v204, v151
	v_pk_add_f32 v[152:153], v[196:197], v[152:153]
	v_cvt_pk_bf16_f32 v161, v187, v189
	v_pk_add_f32 v[152:153], v[198:199], v[152:153]
	v_cvt_pk_bf16_f32 v186, v191, v193
	v_pk_add_f32 v[152:153], v[200:201], v[152:153]
	v_cvt_pk_bf16_f32 v187, v195, v197
	v_pk_add_f32 v[152:153], v[202:203], v[152:153]
	v_cvt_pk_bf16_f32 v188, v199, v201
	v_pk_add_f32 v[152:153], v[204:205], v[152:153]
	v_cvt_pk_bf16_f32 v189, v203, v205
	v_pk_add_f32 v[120:121], v[120:121], v[152:153]
	v_cvt_pk_bf16_f32 v152, v190, v192
	v_cvt_pk_bf16_f32 v153, v194, v196
	v_cvt_pk_bf16_f32 v154, v198, v200
	v_cvt_pk_bf16_f32 v155, v202, v204
	s_setprio 1
	s_waitcnt lgkmcnt(3)
	v_mfma_f32_16x16x32_bf16 v[34:37], v[168:171], v[160:163], v[34:37]
	s_waitcnt lgkmcnt(2)
	v_mfma_f32_16x16x32_bf16 v[38:41], v[172:175], v[160:163], v[38:41]
	s_waitcnt lgkmcnt(1)
	v_mfma_f32_16x16x32_bf16 v[42:45], v[176:179], v[160:163], v[42:45]
	s_waitcnt lgkmcnt(0)
	v_mfma_f32_16x16x32_bf16 v[46:49], v[182:185], v[160:163], v[46:49]
	v_mfma_f32_16x16x32_bf16 v[50:53], v[168:171], v[164:167], v[50:53]
	v_mfma_f32_16x16x32_bf16 v[54:57], v[172:175], v[164:167], v[54:57]
	v_mfma_f32_16x16x32_bf16 v[58:61], v[176:179], v[164:167], v[58:61]
	v_mfma_f32_16x16x32_bf16 v[62:65], v[182:185], v[164:167], v[62:65]
	v_mfma_f32_16x16x32_bf16 v[66:69], v[168:171], v[186:189], v[66:69]
	v_mfma_f32_16x16x32_bf16 v[70:73], v[172:175], v[186:189], v[70:73]
	v_mfma_f32_16x16x32_bf16 v[74:77], v[176:179], v[186:189], v[74:77]
	v_mfma_f32_16x16x32_bf16 v[78:81], v[182:185], v[186:189], v[78:81]
	v_mfma_f32_16x16x32_bf16 v[82:85], v[168:171], v[152:155], v[82:85]
	v_mfma_f32_16x16x32_bf16 v[86:89], v[172:175], v[152:155], v[86:89]
	v_mfma_f32_16x16x32_bf16 v[90:93], v[176:179], v[152:155], v[90:93]
	v_mfma_f32_16x16x32_bf16 v[94:97], v[182:185], v[152:155], v[94:97]
	s_setprio 0
	s_mov_b32 s20, 1
	s_and_b64 vcc, exec, s[18:19]
	s_mov_b64 s[18:19], 0
	s_cbranch_vccnz .LBB0_2477
.LBB0_2479:
	s_or_b64 exec, exec, s[76:77]
	s_andn2_b64 vcc, exec, s[74:75]
	s_cbranch_vccnz .LBB0_2481
	s_bitcmp1_b32 s53, 0
	s_cselect_b32 s16, 0x4800, 0
	v_add_u32_e32 v180, s16, v145
	v_add3_u32 v236, v180, v219, v220
	v_add3_u32 v180, v180, v221, v220
	s_waitcnt vmcnt(1)
	ds_write_b128 v236, v[102:105]
	s_waitcnt vmcnt(0)
	ds_write_b128 v180, v[98:101] offset:9216

.Lnsa_selx_0:
	v_mov_b32_e32 v149, v97
	v_mov_b32_e32 v148, v96
	v_mov_b32_e32 v151, v95
	v_mov_b32_e32 v150, v94
	v_mov_b32_e32 v153, v93
	v_mov_b32_e32 v152, v92
	v_mov_b32_e32 v155, v91
	v_mov_b32_e32 v154, v90
	v_mov_b32_e32 v157, v89
	v_mov_b32_e32 v156, v88
	v_mov_b32_e32 v159, v87
	v_mov_b32_e32 v158, v86
	v_mov_b32_e32 v161, v85
	v_mov_b32_e32 v160, v84
	v_mov_b32_e32 v163, v83
	v_mov_b32_e32 v162, v82
	v_mov_b32_e32 v165, v81
	v_mov_b32_e32 v164, v80
	v_mov_b32_e32 v167, v79
	v_mov_b32_e32 v166, v78
	v_mov_b32_e32 v169, v77
	v_mov_b32_e32 v168, v76
	v_mov_b32_e32 v171, v75
	v_mov_b32_e32 v170, v74
	v_mov_b32_e32 v173, v73
	v_mov_b32_e32 v172, v72
	v_mov_b32_e32 v175, v71
	v_mov_b32_e32 v174, v70
	v_mov_b32_e32 v177, v69
	v_mov_b32_e32 v176, v68
	v_mov_b32_e32 v179, v67
	v_mov_b32_e32 v178, v66
	v_mov_b32_e32 v199, v37
	v_mov_b32_e32 v198, v36
	v_mov_b32_e32 v201, v35
	v_mov_b32_e32 v200, v34
	v_mov_b32_e32 v203, v41
	v_mov_b32_e32 v202, v40
	v_mov_b32_e32 v205, v39
	v_mov_b32_e32 v204, v38
	v_mov_b32_e32 v207, v45
	v_mov_b32_e32 v206, v44
	v_mov_b32_e32 v209, v43
	v_mov_b32_e32 v208, v42
	v_mov_b32_e32 v211, v49
	v_mov_b32_e32 v210, v48
	v_mov_b32_e32 v213, v47
	v_mov_b32_e32 v212, v46
	v_mov_b32_e32 v183, v53
	v_mov_b32_e32 v182, v52
	v_mov_b32_e32 v185, v51
	v_mov_b32_e32 v184, v50
	v_mov_b32_e32 v187, v57
	v_mov_b32_e32 v186, v56
	v_mov_b32_e32 v189, v55
	v_mov_b32_e32 v188, v54
	v_mov_b32_e32 v191, v61
	v_mov_b32_e32 v190, v60
	v_mov_b32_e32 v193, v59
	v_mov_b32_e32 v192, v58
	v_mov_b32_e32 v195, v65
	v_mov_b32_e32 v194, v64
	v_mov_b32_e32 v197, v63
	v_mov_b32_e32 v196, v62
	s_branch .LBB0_2486

.LBB0_2689:
	s_lshl_b32 s21, s20, 5
	v_or_b32_e32 v151, s21, v226
	v_mad_u32_u24 v151, v151, s52, v148
	ds_read_b128 v[152:155], v151
	ds_read_b128 v[156:159], v151 offset:64
	ds_read_b128 v[160:163], v151 offset:2304
	ds_read_b128 v[164:167], v151 offset:2368
	v_lshl_add_u32 v151, s20, 6, v149
	ds_read_b128 v[168:171], v151 offset:9216
	ds_read_b128 v[172:175], v151 offset:11520
	ds_read_b128 v[176:179], v151 offset:13824
	ds_read_b128 v[182:185], v151 offset:16128
	v_add_u32_e32 v151, s21, v150
	v_sub_u32_e32 v180, v227, v151
	v_cmp_gt_u32_e32 vcc, 2.0, v180
	v_cvt_f32_i32_e32 v180, v180
	v_xad_u32 v186, v151, -1, v227
	v_cvt_f32_i32_e32 v187, v186
	s_and_b64 vcc, s[16:17], vcc
	v_cndmask_b32_e32 v180, v233, v180, vcc
	v_cmp_gt_u32_e32 vcc, 2.0, v186
	v_or_b32_e32 v186, 2, v151
	s_and_b64 vcc, s[16:17], vcc
	v_sub_u32_e32 v186, v227, v186
	v_cndmask_b32_e32 v234, v233, v187, vcc
	v_cmp_gt_u32_e32 vcc, 2.0, v186
	v_cvt_f32_i32_e32 v186, v186
	v_or_b32_e32 v187, 3, v151
	v_sub_u32_e32 v187, v227, v187
	v_cvt_f32_i32_e32 v188, v187
	s_and_b64 vcc, s[16:17], vcc
	v_cndmask_b32_e32 v235, v233, v186, vcc
	v_cmp_gt_u32_e32 vcc, 2.0, v187
	v_or_b32_e32 v186, 4, v151
	s_and_b64 vcc, s[16:17], vcc
	v_sub_u32_e32 v186, v227, v186
	v_cndmask_b32_e32 v236, v233, v188, vcc
	v_cmp_gt_u32_e32 vcc, 2.0, v186
	v_cvt_f32_i32_e32 v186, v186
	v_or_b32_e32 v187, 5, v151
	v_sub_u32_e32 v187, v227, v187
	v_cvt_f32_i32_e32 v188, v187
	s_and_b64 vcc, s[16:17], vcc
	v_cndmask_b32_e32 v237, v233, v186, vcc
	v_cmp_gt_u32_e32 vcc, 2.0, v187
	v_or_b32_e32 v186, 6, v151
	s_and_b64 vcc, s[16:17], vcc
	v_sub_u32_e32 v186, v227, v186
	v_cndmask_b32_e32 v238, v233, v188, vcc
	v_cmp_gt_u32_e32 vcc, 2.0, v186
	v_cvt_f32_i32_e32 v186, v186
	v_or_b32_e32 v151, 7, v151
	v_sub_u32_e32 v151, v227, v151
	v_cvt_f32_i32_e32 v187, v151
	s_and_b64 vcc, s[16:17], vcc
	v_cndmask_b32_e32 v239, v233, v186, vcc
	v_cmp_gt_u32_e32 vcc, 2.0, v151
	s_and_b64 vcc, s[16:17], vcc
	s_nop 0
	v_cndmask_b32_e32 v151, v233, v187, vcc
	s_setprio 1
	s_waitcnt lgkmcnt(7)
	v_mfma_f32_16x16x32_bf16 v[186:189], v[152:155], v[2:5], 0
	v_mfma_f32_16x16x32_bf16 v[194:197], v[152:155], v[10:13], 0
	v_mfma_f32_16x16x32_bf16 v[202:205], v[152:155], v[18:21], 0
	v_mfma_f32_16x16x32_bf16 v[152:155], v[152:155], v[26:29], 0
	s_waitcnt lgkmcnt(6)
	v_mfma_f32_16x16x32_bf16 v[186:189], v[156:159], v[6:9], v[186:189]
	s_waitcnt lgkmcnt(5)
	v_mfma_f32_16x16x32_bf16 v[190:193], v[160:163], v[2:5], 0
	v_mfma_f32_16x16x32_bf16 v[194:197], v[156:159], v[14:17], v[194:197]
	v_mfma_f32_16x16x32_bf16 v[198:201], v[160:163], v[10:13], 0
	v_mfma_f32_16x16x32_bf16 v[202:205], v[156:159], v[22:25], v[202:205]
	v_mfma_f32_16x16x32_bf16 v[206:209], v[160:163], v[18:21], 0
	v_mfma_f32_16x16x32_bf16 v[152:155], v[156:159], v[30:33], v[152:155]
	v_mfma_f32_16x16x32_bf16 v[156:159], v[160:163], v[26:29], 0
	s_waitcnt lgkmcnt(4)
	v_mfma_f32_16x16x32_bf16 v[190:193], v[164:167], v[6:9], v[190:193]
	v_mfma_f32_16x16x32_bf16 v[198:201], v[164:167], v[14:17], v[198:201]
	v_mfma_f32_16x16x32_bf16 v[206:209], v[164:167], v[22:25], v[206:209]
	v_mfma_f32_16x16x32_bf16 v[156:159], v[164:167], v[30:33], v[156:159]
	s_setprio 0
	v_fma_f32 v160, -v215, v180, v186
	v_fma_f32 v164, -v216, v180, v194
	v_exp_f32_e32 v165, v160
	v_fma_f32 v160, -v215, v234, v187
	v_exp_f32_e32 v164, v164
	v_fma_f32 v166, -v216, v234, v195
	v_exp_f32_e32 v167, v160
	v_fma_f32 v160, -v215, v235, v188
	v_exp_f32_e32 v166, v166
	v_fma_f32 v186, -v216, v235, v196
	v_exp_f32_e32 v187, v160
	v_fma_f32 v160, -v215, v236, v189
	v_exp_f32_e32 v186, v186
	v_fma_f32 v188, -v216, v236, v197
	v_exp_f32_e32 v189, v160
	v_fma_f32 v160, -v215, v237, v190
	v_exp_f32_e32 v188, v188
	v_fma_f32 v190, -v216, v237, v198
	v_exp_f32_e32 v211, v160
	v_fma_f32 v160, -v215, v238, v191
	v_exp_f32_e32 v210, v190
	v_fma_f32 v190, -v216, v238, v199
	v_pk_add_f32 v[194:195], v[164:165], 0 op_sel_hi:[1,0]
	v_exp_f32_e32 v191, v160
	v_fma_f32 v160, -v215, v239, v192
	v_exp_f32_e32 v190, v190
	v_fma_f32 v192, -v216, v239, v200
	v_pk_add_f32 v[194:195], v[166:167], v[194:195]
	v_exp_f32_e32 v213, v160
	v_fma_f32 v160, -v215, v151, v193
	v_exp_f32_e32 v212, v192
	v_fma_f32 v192, -v216, v151, v201
	v_pk_add_f32 v[194:195], v[186:187], v[194:195]
	v_exp_f32_e32 v193, v160
	v_exp_f32_e32 v192, v192
	v_pk_add_f32 v[194:195], v[188:189], v[194:195]
	v_fma_f32 v152, -v218, v180, v152
	v_pk_add_f32 v[194:195], v[210:211], v[194:195]
	v_cvt_pk_bf16_f32 v164, v164, v166
	v_pk_add_f32 v[194:195], v[190:191], v[194:195]
	v_cvt_pk_bf16_f32 v166, v210, v190
	v_pk_add_f32 v[194:195], v[212:213], v[194:195]
	v_exp_f32_e32 v190, v152
	v_fma_f32 v152, -v218, v234, v153
	v_cvt_pk_bf16_f32 v160, v165, v167
	v_pk_add_f32 v[194:195], v[192:193], v[194:195]
	v_cvt_pk_bf16_f32 v165, v186, v188
	v_cvt_pk_bf16_f32 v167, v212, v192
	v_fma_f32 v186, -v217, v180, v202
	v_exp_f32_e32 v192, v152
	v_fma_f32 v152, -v218, v235, v154
	v_cvt_pk_bf16_f32 v162, v211, v191
	v_pk_add_f32 v[122:123], v[122:123], v[194:195]
	v_exp_f32_e32 v191, v186
	v_fma_f32 v186, -v217, v234, v203
	v_exp_f32_e32 v194, v152
	v_fma_f32 v152, -v218, v236, v155
	v_cvt_pk_bf16_f32 v163, v213, v193
	v_exp_f32_e32 v193, v186
	v_fma_f32 v186, -v217, v235, v204
	v_exp_f32_e32 v196, v152
	v_fma_f32 v152, -v218, v237, v156
	v_exp_f32_e32 v195, v186
	v_fma_f32 v186, -v217, v236, v205
	v_exp_f32_e32 v198, v152
	v_fma_f32 v152, -v218, v238, v157
	v_exp_f32_e32 v197, v186
	v_fma_f32 v186, -v217, v237, v206
	v_exp_f32_e32 v200, v152
	v_fma_f32 v152, -v218, v239, v158
	v_exp_f32_e32 v199, v186
	v_fma_f32 v186, -v217, v238, v207
	v_exp_f32_e32 v202, v152
	v_pk_add_f32 v[152:153], v[190:191], 0 op_sel_hi:[1,0]
	v_exp_f32_e32 v201, v186
	v_fma_f32 v186, -v217, v239, v208
	v_pk_add_f32 v[152:153], v[192:193], v[152:153]
	v_exp_f32_e32 v203, v186
	v_fma_f32 v186, -v217, v151, v209
	v_fma_f32 v151, -v218, v151, v159
	v_pk_add_f32 v[152:153], v[194:195], v[152:153]
	v_exp_f32_e32 v205, v186
	v_exp_f32_e32 v204, v151
	v_pk_add_f32 v[152:153], v[196:197], v[152:153]
	v_cvt_pk_bf16_f32 v161, v187, v189
	v_pk_add_f32 v[152:153], v[198:199], v[152:153]
	v_cvt_pk_bf16_f32 v186, v191, v193
	v_pk_add_f32 v[152:153], v[200:201], v[152:153]
	v_cvt_pk_bf16_f32 v187, v195, v197
	v_pk_add_f32 v[152:153], v[202:203], v[152:153]
	v_cvt_pk_bf16_f32 v188, v199, v201
	v_pk_add_f32 v[152:153], v[204:205], v[152:153]
	v_cvt_pk_bf16_f32 v189, v203, v205
	v_pk_add_f32 v[120:121], v[120:121], v[152:153]
	v_cvt_pk_bf16_f32 v152, v190, v192
	v_cvt_pk_bf16_f32 v153, v194, v196
	v_cvt_pk_bf16_f32 v154, v198, v200
	v_cvt_pk_bf16_f32 v155, v202, v204
	s_setprio 1
	s_waitcnt lgkmcnt(3)
	v_mfma_f32_16x16x32_bf16 v[34:37], v[168:171], v[160:163], v[34:37]
	s_waitcnt lgkmcnt(2)
	v_mfma_f32_16x16x32_bf16 v[38:41], v[172:175], v[160:163], v[38:41]
	s_waitcnt lgkmcnt(1)
	v_mfma_f32_16x16x32_bf16 v[42:45], v[176:179], v[160:163], v[42:45]
	s_waitcnt lgkmcnt(0)
	v_mfma_f32_16x16x32_bf16 v[46:49], v[182:185], v[160:163], v[46:49]
	v_mfma_f32_16x16x32_bf16 v[50:53], v[168:171], v[164:167], v[50:53]
	v_mfma_f32_16x16x32_bf16 v[54:57], v[172:175], v[164:167], v[54:57]
	v_mfma_f32_16x16x32_bf16 v[58:61], v[176:179], v[164:167], v[58:61]
	v_mfma_f32_16x16x32_bf16 v[62:65], v[182:185], v[164:167], v[62:65]
	v_mfma_f32_16x16x32_bf16 v[66:69], v[168:171], v[186:189], v[66:69]
	v_mfma_f32_16x16x32_bf16 v[70:73], v[172:175], v[186:189], v[70:73]
	v_mfma_f32_16x16x32_bf16 v[74:77], v[176:179], v[186:189], v[74:77]
	v_mfma_f32_16x16x32_bf16 v[78:81], v[182:185], v[186:189], v[78:81]
	v_mfma_f32_16x16x32_bf16 v[82:85], v[168:171], v[152:155], v[82:85]
	v_mfma_f32_16x16x32_bf16 v[86:89], v[172:175], v[152:155], v[86:89]
	v_mfma_f32_16x16x32_bf16 v[90:93], v[176:179], v[152:155], v[90:93]
	v_mfma_f32_16x16x32_bf16 v[94:97], v[182:185], v[152:155], v[94:97]
	s_setprio 0
	s_mov_b32 s20, 1
	s_and_b64 vcc, exec, s[18:19]
	s_mov_b64 s[18:19], 0
	s_cbranch_vccnz .LBB0_2689
.LBB0_2691:
	s_or_b64 exec, exec, s[66:67]
	s_andn2_b64 vcc, exec, s[64:65]
	s_cbranch_vccnz .LBB0_2693
	s_bitcmp1_b32 s53, 0
	s_cselect_b32 s16, 0x4800, 0
	v_add_u32_e32 v180, s16, v145
	v_add3_u32 v234, v180, v219, v220
	v_add3_u32 v180, v180, v221, v220
	s_waitcnt vmcnt(1)
	ds_write_b128 v234, v[102:105]
	s_waitcnt vmcnt(0)
	ds_write_b128 v180, v[98:101] offset:9216

.LBB0_2903:
	s_lshl_b32 s21, s20, 5
	v_or_b32_e32 v151, s21, v226
	v_mad_u32_u24 v151, v151, s46, v148
	ds_read_b128 v[152:155], v151
	ds_read_b128 v[156:159], v151 offset:64
	ds_read_b128 v[160:163], v151 offset:2304
	ds_read_b128 v[164:167], v151 offset:2368
	v_lshl_add_u32 v151, s20, 6, v149
	ds_read_b128 v[168:171], v151 offset:9216
	ds_read_b128 v[172:175], v151 offset:11520
	ds_read_b128 v[176:179], v151 offset:13824
	ds_read_b128 v[182:185], v151 offset:16128
	v_add_u32_e32 v151, s21, v150
	v_sub_u32_e32 v180, v227, v151
	v_cmp_gt_u32_e32 vcc, 2.0, v180
	v_cvt_f32_i32_e32 v180, v180
	v_xad_u32 v186, v151, -1, v227
	v_cvt_f32_i32_e32 v187, v186
	s_and_b64 vcc, s[16:17], vcc
	v_cndmask_b32_e32 v180, v236, v180, vcc
	v_cmp_gt_u32_e32 vcc, 2.0, v186
	v_or_b32_e32 v186, 2, v151
	s_and_b64 vcc, s[16:17], vcc
	v_sub_u32_e32 v186, v227, v186
	v_cndmask_b32_e32 v237, v236, v187, vcc
	v_cmp_gt_u32_e32 vcc, 2.0, v186
	v_cvt_f32_i32_e32 v186, v186
	v_or_b32_e32 v187, 3, v151
	v_sub_u32_e32 v187, v227, v187
	v_cvt_f32_i32_e32 v188, v187
	s_and_b64 vcc, s[16:17], vcc
	v_cndmask_b32_e32 v238, v236, v186, vcc
	v_cmp_gt_u32_e32 vcc, 2.0, v187
	v_or_b32_e32 v186, 4, v151
	s_and_b64 vcc, s[16:17], vcc
	v_sub_u32_e32 v186, v227, v186
	v_cndmask_b32_e32 v239, v236, v188, vcc
	v_cmp_gt_u32_e32 vcc, 2.0, v186
	v_cvt_f32_i32_e32 v186, v186
	v_or_b32_e32 v187, 5, v151
	v_sub_u32_e32 v187, v227, v187
	v_cvt_f32_i32_e32 v188, v187
	s_and_b64 vcc, s[16:17], vcc
	v_cndmask_b32_e32 v240, v236, v186, vcc
	v_cmp_gt_u32_e32 vcc, 2.0, v187
	v_or_b32_e32 v186, 6, v151
	s_and_b64 vcc, s[16:17], vcc
	v_sub_u32_e32 v186, v227, v186
	v_cndmask_b32_e32 v241, v236, v188, vcc
	v_cmp_gt_u32_e32 vcc, 2.0, v186
	v_cvt_f32_i32_e32 v186, v186
	v_or_b32_e32 v151, 7, v151
	v_sub_u32_e32 v151, v227, v151
	v_cvt_f32_i32_e32 v187, v151
	s_and_b64 vcc, s[16:17], vcc
	v_cndmask_b32_e32 v242, v236, v186, vcc
	v_cmp_gt_u32_e32 vcc, 2.0, v151
	s_and_b64 vcc, s[16:17], vcc
	s_nop 0
	v_cndmask_b32_e32 v151, v236, v187, vcc
	s_setprio 1
	s_waitcnt lgkmcnt(7)
	v_mfma_f32_16x16x32_bf16 v[186:189], v[152:155], v[2:5], 0
	v_mfma_f32_16x16x32_bf16 v[194:197], v[152:155], v[10:13], 0
	v_mfma_f32_16x16x32_bf16 v[202:205], v[152:155], v[18:21], 0
	v_mfma_f32_16x16x32_bf16 v[152:155], v[152:155], v[26:29], 0
	s_waitcnt lgkmcnt(6)
	v_mfma_f32_16x16x32_bf16 v[186:189], v[156:159], v[6:9], v[186:189]
	s_waitcnt lgkmcnt(5)
	v_mfma_f32_16x16x32_bf16 v[190:193], v[160:163], v[2:5], 0
	v_mfma_f32_16x16x32_bf16 v[194:197], v[156:159], v[14:17], v[194:197]
	v_mfma_f32_16x16x32_bf16 v[198:201], v[160:163], v[10:13], 0
	v_mfma_f32_16x16x32_bf16 v[202:205], v[156:159], v[22:25], v[202:205]
	v_mfma_f32_16x16x32_bf16 v[206:209], v[160:163], v[18:21], 0
	v_mfma_f32_16x16x32_bf16 v[152:155], v[156:159], v[30:33], v[152:155]
	v_mfma_f32_16x16x32_bf16 v[156:159], v[160:163], v[26:29], 0
	s_waitcnt lgkmcnt(4)
	v_mfma_f32_16x16x32_bf16 v[190:193], v[164:167], v[6:9], v[190:193]
	v_mfma_f32_16x16x32_bf16 v[198:201], v[164:167], v[14:17], v[198:201]
	v_mfma_f32_16x16x32_bf16 v[206:209], v[164:167], v[22:25], v[206:209]
	v_mfma_f32_16x16x32_bf16 v[156:159], v[164:167], v[30:33], v[156:159]
	s_setprio 0
	v_fma_f32 v160, -v215, v180, v186
	v_fma_f32 v164, -v216, v180, v194
	v_exp_f32_e32 v165, v160
	v_fma_f32 v160, -v215, v237, v187
	v_exp_f32_e32 v164, v164
	v_fma_f32 v166, -v216, v237, v195
	v_exp_f32_e32 v167, v160
	v_fma_f32 v160, -v215, v238, v188
	v_exp_f32_e32 v166, v166
	v_fma_f32 v186, -v216, v238, v196
	v_exp_f32_e32 v187, v160
	v_fma_f32 v160, -v215, v239, v189
	v_exp_f32_e32 v186, v186
	v_fma_f32 v188, -v216, v239, v197
	v_exp_f32_e32 v189, v160
	v_fma_f32 v160, -v215, v240, v190
	v_exp_f32_e32 v188, v188
	v_fma_f32 v190, -v216, v240, v198
	v_exp_f32_e32 v211, v160
	v_fma_f32 v160, -v215, v241, v191
	v_exp_f32_e32 v210, v190
	v_fma_f32 v190, -v216, v241, v199
	v_pk_add_f32 v[194:195], v[164:165], 0 op_sel_hi:[1,0]
	v_exp_f32_e32 v191, v160
	v_fma_f32 v160, -v215, v242, v192
	v_exp_f32_e32 v190, v190
	v_fma_f32 v192, -v216, v242, v200
	v_pk_add_f32 v[194:195], v[166:167], v[194:195]
	v_exp_f32_e32 v213, v160
	v_fma_f32 v160, -v215, v151, v193
	v_exp_f32_e32 v212, v192
	v_fma_f32 v192, -v216, v151, v201
	v_pk_add_f32 v[194:195], v[186:187], v[194:195]
	v_exp_f32_e32 v193, v160
	v_exp_f32_e32 v192, v192
	v_pk_add_f32 v[194:195], v[188:189], v[194:195]
	v_fma_f32 v152, -v218, v180, v152
	v_pk_add_f32 v[194:195], v[210:211], v[194:195]
	v_cvt_pk_bf16_f32 v164, v164, v166
	v_pk_add_f32 v[194:195], v[190:191], v[194:195]
	v_cvt_pk_bf16_f32 v166, v210, v190
	v_pk_add_f32 v[194:195], v[212:213], v[194:195]
	v_exp_f32_e32 v190, v152
	v_fma_f32 v152, -v218, v237, v153
	v_cvt_pk_bf16_f32 v160, v165, v167
	v_pk_add_f32 v[194:195], v[192:193], v[194:195]
	v_cvt_pk_bf16_f32 v165, v186, v188
	v_cvt_pk_bf16_f32 v167, v212, v192
	v_fma_f32 v186, -v217, v180, v202
	v_exp_f32_e32 v192, v152
	v_fma_f32 v152, -v218, v238, v154
	v_cvt_pk_bf16_f32 v162, v211, v191
	v_pk_add_f32 v[122:123], v[122:123], v[194:195]
	v_exp_f32_e32 v191, v186
	v_fma_f32 v186, -v217, v237, v203
	v_exp_f32_e32 v194, v152
	v_fma_f32 v152, -v218, v239, v155
	v_cvt_pk_bf16_f32 v163, v213, v193
	v_exp_f32_e32 v193, v186
	v_fma_f32 v186, -v217, v238, v204
	v_exp_f32_e32 v196, v152
	v_fma_f32 v152, -v218, v240, v156
	v_exp_f32_e32 v195, v186
	v_fma_f32 v186, -v217, v239, v205
	v_exp_f32_e32 v198, v152
	v_fma_f32 v152, -v218, v241, v157
	v_exp_f32_e32 v197, v186
	v_fma_f32 v186, -v217, v240, v206
	v_exp_f32_e32 v200, v152
	v_fma_f32 v152, -v218, v242, v158
	v_exp_f32_e32 v199, v186
	v_fma_f32 v186, -v217, v241, v207
	v_exp_f32_e32 v202, v152
	v_pk_add_f32 v[152:153], v[190:191], 0 op_sel_hi:[1,0]
	v_exp_f32_e32 v201, v186
	v_fma_f32 v186, -v217, v242, v208
	v_pk_add_f32 v[152:153], v[192:193], v[152:153]
	v_exp_f32_e32 v203, v186
	v_fma_f32 v186, -v217, v151, v209
	v_fma_f32 v151, -v218, v151, v159
	v_pk_add_f32 v[152:153], v[194:195], v[152:153]
	v_exp_f32_e32 v205, v186
	v_exp_f32_e32 v204, v151
	v_pk_add_f32 v[152:153], v[196:197], v[152:153]
	v_cvt_pk_bf16_f32 v161, v187, v189
	v_pk_add_f32 v[152:153], v[198:199], v[152:153]
	v_cvt_pk_bf16_f32 v186, v191, v193
	v_pk_add_f32 v[152:153], v[200:201], v[152:153]
	v_cvt_pk_bf16_f32 v187, v195, v197
	v_pk_add_f32 v[152:153], v[202:203], v[152:153]
	v_cvt_pk_bf16_f32 v188, v199, v201
	v_pk_add_f32 v[152:153], v[204:205], v[152:153]
	v_cvt_pk_bf16_f32 v189, v203, v205
	v_pk_add_f32 v[120:121], v[120:121], v[152:153]
	v_cvt_pk_bf16_f32 v152, v190, v192
	v_cvt_pk_bf16_f32 v153, v194, v196
	v_cvt_pk_bf16_f32 v154, v198, v200
	v_cvt_pk_bf16_f32 v155, v202, v204
	s_setprio 1
	s_waitcnt lgkmcnt(3)
	v_mfma_f32_16x16x32_bf16 v[34:37], v[168:171], v[160:163], v[34:37]
	s_waitcnt lgkmcnt(2)
	v_mfma_f32_16x16x32_bf16 v[38:41], v[172:175], v[160:163], v[38:41]
	s_waitcnt lgkmcnt(1)
	v_mfma_f32_16x16x32_bf16 v[42:45], v[176:179], v[160:163], v[42:45]
	s_waitcnt lgkmcnt(0)
	v_mfma_f32_16x16x32_bf16 v[46:49], v[182:185], v[160:163], v[46:49]
	v_mfma_f32_16x16x32_bf16 v[50:53], v[168:171], v[164:167], v[50:53]
	v_mfma_f32_16x16x32_bf16 v[54:57], v[172:175], v[164:167], v[54:57]
	v_mfma_f32_16x16x32_bf16 v[58:61], v[176:179], v[164:167], v[58:61]
	v_mfma_f32_16x16x32_bf16 v[62:65], v[182:185], v[164:167], v[62:65]
	v_mfma_f32_16x16x32_bf16 v[66:69], v[168:171], v[186:189], v[66:69]
	v_mfma_f32_16x16x32_bf16 v[70:73], v[172:175], v[186:189], v[70:73]
	v_mfma_f32_16x16x32_bf16 v[74:77], v[176:179], v[186:189], v[74:77]
	v_mfma_f32_16x16x32_bf16 v[78:81], v[182:185], v[186:189], v[78:81]
	v_mfma_f32_16x16x32_bf16 v[82:85], v[168:171], v[152:155], v[82:85]
	v_mfma_f32_16x16x32_bf16 v[86:89], v[172:175], v[152:155], v[86:89]
	v_mfma_f32_16x16x32_bf16 v[90:93], v[176:179], v[152:155], v[90:93]
	v_mfma_f32_16x16x32_bf16 v[94:97], v[182:185], v[152:155], v[94:97]
	s_setprio 0
	s_mov_b32 s20, 1
	s_and_b64 vcc, exec, s[18:19]
	s_mov_b64 s[18:19], 0
	s_cbranch_vccnz .LBB0_2903
.LBB0_2905:
	s_or_b64 exec, exec, s[76:77]
	s_andn2_b64 vcc, exec, s[74:75]
	s_cbranch_vccnz .LBB0_2907
	s_bitcmp1_b32 s47, 0
	s_cselect_b32 s16, 0x4800, 0
	v_add_u32_e32 v180, s16, v145
	v_add3_u32 v237, v180, v219, v220
	v_add3_u32 v180, v180, v221, v220
	s_waitcnt vmcnt(1)
	ds_write_b128 v237, v[102:105]
	s_waitcnt vmcnt(0)
	ds_write_b128 v180, v[98:101] offset:9216

.LBB0_3106:
	s_lshl_b32 s7, s6, 5
	v_or_b32_e32 v141, s7, v208
	v_mad_u32_u24 v141, v141, s13, v138
	ds_read_b128 v[148:151], v141
	ds_read_b128 v[152:155], v141 offset:64
	ds_read_b128 v[156:159], v141 offset:2304
	ds_read_b128 v[160:163], v141 offset:2368
	v_lshl_add_u32 v141, s6, 6, v139
	ds_read_b128 v[164:167], v141 offset:9216
	ds_read_b128 v[168:171], v141 offset:11520
	ds_read_b128 v[176:179], v141 offset:13824
	ds_read_b128 v[180:183], v141 offset:16128
	v_add_u32_e32 v141, s7, v140
	v_sub_u32_e32 v142, v209, v141
	v_cmp_gt_u32_e32 vcc, 2.0, v142
	v_cvt_f32_i32_e32 v142, v142
	v_xad_u32 v143, v141, -1, v209
	v_cvt_f32_i32_e32 v172, v143
	s_and_b64 vcc, s[0:1], vcc
	v_cndmask_b32_e32 v174, v222, v142, vcc
	v_cmp_gt_u32_e32 vcc, 2.0, v143
	v_or_b32_e32 v142, 2, v141
	s_and_b64 vcc, s[0:1], vcc
	v_sub_u32_e32 v142, v209, v142
	v_cndmask_b32_e32 v223, v222, v172, vcc
	v_cmp_gt_u32_e32 vcc, 2.0, v142
	v_cvt_f32_i32_e32 v142, v142
	v_or_b32_e32 v143, 3, v141
	v_sub_u32_e32 v143, v209, v143
	v_cvt_f32_i32_e32 v172, v143
	s_and_b64 vcc, s[0:1], vcc
	v_cndmask_b32_e32 v226, v222, v142, vcc
	v_cmp_gt_u32_e32 vcc, 2.0, v143
	v_or_b32_e32 v142, 4, v141
	s_and_b64 vcc, s[0:1], vcc
	v_sub_u32_e32 v142, v209, v142
	v_cndmask_b32_e32 v227, v222, v172, vcc
	v_cmp_gt_u32_e32 vcc, 2.0, v142
	v_cvt_f32_i32_e32 v142, v142
	v_or_b32_e32 v143, 5, v141
	v_sub_u32_e32 v143, v209, v143
	v_cvt_f32_i32_e32 v172, v143
	s_and_b64 vcc, s[0:1], vcc
	v_cndmask_b32_e32 v228, v222, v142, vcc
	v_cmp_gt_u32_e32 vcc, 2.0, v143
	v_or_b32_e32 v142, 6, v141
	s_and_b64 vcc, s[0:1], vcc
	v_sub_u32_e32 v142, v209, v142
	v_cndmask_b32_e32 v229, v222, v172, vcc
	v_cmp_gt_u32_e32 vcc, 2.0, v142
	v_cvt_f32_i32_e32 v142, v142
	v_or_b32_e32 v141, 7, v141
	v_sub_u32_e32 v141, v209, v141
	v_cvt_f32_i32_e32 v143, v141
	s_and_b64 vcc, s[0:1], vcc
	v_cndmask_b32_e32 v230, v222, v142, vcc
	v_cmp_gt_u32_e32 vcc, 2.0, v141
	s_and_b64 vcc, s[0:1], vcc
	s_nop 0
	v_cndmask_b32_e32 v141, v222, v143, vcc
	s_setprio 1
	s_waitcnt lgkmcnt(7)
	v_mfma_f32_16x16x32_bf16 v[184:187], v[148:151], v[2:5], 0
	v_mfma_f32_16x16x32_bf16 v[192:195], v[148:151], v[10:13], 0
	v_mfma_f32_16x16x32_bf16 v[200:203], v[148:151], v[18:21], 0
	v_mfma_f32_16x16x32_bf16 v[148:151], v[148:151], v[26:29], 0
	s_waitcnt lgkmcnt(6)
	v_mfma_f32_16x16x32_bf16 v[184:187], v[152:155], v[6:9], v[184:187]
	s_waitcnt lgkmcnt(5)
	v_mfma_f32_16x16x32_bf16 v[188:191], v[156:159], v[2:5], 0
	v_mfma_f32_16x16x32_bf16 v[192:195], v[152:155], v[14:17], v[192:195]
	v_mfma_f32_16x16x32_bf16 v[196:199], v[156:159], v[10:13], 0
	v_mfma_f32_16x16x32_bf16 v[200:203], v[152:155], v[22:25], v[200:203]
	v_mfma_f32_16x16x32_bf16 v[204:207], v[156:159], v[18:21], 0
	v_mfma_f32_16x16x32_bf16 v[148:151], v[152:155], v[30:33], v[148:151]
	v_mfma_f32_16x16x32_bf16 v[152:155], v[156:159], v[26:29], 0
	s_waitcnt lgkmcnt(4)
	v_mfma_f32_16x16x32_bf16 v[188:191], v[160:163], v[6:9], v[188:191]
	v_mfma_f32_16x16x32_bf16 v[196:199], v[160:163], v[14:17], v[196:199]
	v_mfma_f32_16x16x32_bf16 v[204:207], v[160:163], v[22:25], v[204:207]
	v_mfma_f32_16x16x32_bf16 v[152:155], v[160:163], v[30:33], v[152:155]
	s_setprio 0
	v_fma_f32 v142, -v215, v174, v184
	v_exp_f32_e32 v143, v142
	v_fma_f32 v142, -v215, v223, v185
	v_exp_f32_e32 v161, v142
	v_fma_f32 v142, -v215, v226, v186
	v_exp_f32_e32 v163, v142
	v_fma_f32 v142, -v215, v227, v187
	v_exp_f32_e32 v173, v142
	v_fma_f32 v142, -v215, v228, v188
	v_exp_f32_e32 v185, v142
	v_fma_f32 v142, -v215, v229, v189
	v_exp_f32_e32 v187, v142
	v_fma_f32 v142, -v215, v230, v190
	v_exp_f32_e32 v189, v142
	v_fma_f32 v142, -v215, v141, v191
	v_exp_f32_e32 v191, v142
	v_fma_f32 v142, -v216, v174, v192
	v_exp_f32_e32 v142, v142
	v_fma_f32 v160, -v216, v223, v193
	v_exp_f32_e32 v160, v160
	v_fma_f32 v162, -v216, v226, v194
	v_exp_f32_e32 v162, v162
	v_fma_f32 v172, -v216, v227, v195
	v_exp_f32_e32 v172, v172
	v_fma_f32 v184, -v216, v228, v196
	v_exp_f32_e32 v184, v184
	v_fma_f32 v186, -v216, v229, v197
	v_pk_add_f32 v[192:193], v[142:143], 0 op_sel_hi:[1,0]
	v_exp_f32_e32 v186, v186
	v_fma_f32 v188, -v216, v230, v198
	v_pk_add_f32 v[192:193], v[160:161], v[192:193]
	v_exp_f32_e32 v188, v188
	v_fma_f32 v190, -v216, v141, v199
	v_pk_add_f32 v[192:193], v[162:163], v[192:193]
	v_exp_f32_e32 v190, v190
	v_pk_add_f32 v[192:193], v[172:173], v[192:193]
	v_cvt_pk_bf16_f32 v160, v142, v160
	v_fma_f32 v142, -v217, v174, v200
	v_cvt_pk_bf16_f32 v156, v143, v161
	v_pk_add_f32 v[192:193], v[184:185], v[192:193]
	v_exp_f32_e32 v143, v142
	v_fma_f32 v142, -v217, v223, v201
	v_cvt_pk_bf16_f32 v157, v163, v173
	v_pk_add_f32 v[192:193], v[186:187], v[192:193]
	v_exp_f32_e32 v173, v142
	v_fma_f32 v142, -v217, v226, v202
	v_cvt_pk_bf16_f32 v159, v189, v191
	v_pk_add_f32 v[192:193], v[188:189], v[192:193]
	v_exp_f32_e32 v189, v142
	v_fma_f32 v142, -v217, v227, v203
	v_pk_add_f32 v[192:193], v[190:191], v[192:193]
	v_exp_f32_e32 v191, v142
	v_fma_f32 v142, -v217, v228, v204
	v_pk_add_f32 v[122:123], v[122:123], v[192:193]
	v_exp_f32_e32 v193, v142
	v_fma_f32 v142, -v217, v229, v205
	v_exp_f32_e32 v195, v142
	v_fma_f32 v142, -v217, v230, v206
	v_exp_f32_e32 v197, v142
	v_fma_f32 v142, -v217, v141, v207
	v_exp_f32_e32 v199, v142
	v_fma_f32 v142, -v218, v174, v148
	v_fma_f32 v148, -v218, v223, v149
	v_cvt_pk_bf16_f32 v161, v162, v172
	v_exp_f32_e32 v172, v148
	v_fma_f32 v148, -v218, v226, v150
	v_cvt_pk_bf16_f32 v163, v188, v190
	v_exp_f32_e32 v142, v142
	v_exp_f32_e32 v188, v148
	v_fma_f32 v148, -v218, v227, v151
	v_exp_f32_e32 v190, v148
	v_fma_f32 v148, -v218, v228, v152
	v_exp_f32_e32 v192, v148
	v_fma_f32 v148, -v218, v229, v153
	v_exp_f32_e32 v194, v148
	v_fma_f32 v148, -v218, v230, v154
	v_exp_f32_e32 v196, v148
	v_pk_add_f32 v[148:149], v[142:143], 0 op_sel_hi:[1,0]
	v_fma_f32 v141, -v218, v141, v155
	v_pk_add_f32 v[148:149], v[172:173], v[148:149]
	v_exp_f32_e32 v198, v141
	v_pk_add_f32 v[148:149], v[188:189], v[148:149]
	v_cvt_pk_bf16_f32 v158, v185, v187
	v_pk_add_f32 v[148:149], v[190:191], v[148:149]
	v_cvt_pk_bf16_f32 v162, v184, v186
	v_pk_add_f32 v[148:149], v[192:193], v[148:149]
	v_cvt_pk_bf16_f32 v184, v143, v173
	v_pk_add_f32 v[148:149], v[194:195], v[148:149]
	v_cvt_pk_bf16_f32 v185, v189, v191
	v_pk_add_f32 v[148:149], v[196:197], v[148:149]
	v_cvt_pk_bf16_f32 v186, v193, v195
	v_pk_add_f32 v[148:149], v[198:199], v[148:149]
	v_cvt_pk_bf16_f32 v187, v197, v199
	v_pk_add_f32 v[120:121], v[120:121], v[148:149]
	v_cvt_pk_bf16_f32 v148, v142, v172
	v_cvt_pk_bf16_f32 v149, v188, v190
	v_cvt_pk_bf16_f32 v150, v192, v194
	v_cvt_pk_bf16_f32 v151, v196, v198
	s_setprio 1
	s_waitcnt lgkmcnt(3)
	v_mfma_f32_16x16x32_bf16 v[34:37], v[164:167], v[156:159], v[34:37]
	s_waitcnt lgkmcnt(2)
	v_mfma_f32_16x16x32_bf16 v[38:41], v[168:171], v[156:159], v[38:41]
	s_waitcnt lgkmcnt(1)
	v_mfma_f32_16x16x32_bf16 v[42:45], v[176:179], v[156:159], v[42:45]
	s_waitcnt lgkmcnt(0)
	v_mfma_f32_16x16x32_bf16 v[46:49], v[180:183], v[156:159], v[46:49]
	v_mfma_f32_16x16x32_bf16 v[50:53], v[164:167], v[160:163], v[50:53]
	v_mfma_f32_16x16x32_bf16 v[54:57], v[168:171], v[160:163], v[54:57]
	v_mfma_f32_16x16x32_bf16 v[58:61], v[176:179], v[160:163], v[58:61]
	v_mfma_f32_16x16x32_bf16 v[62:65], v[180:183], v[160:163], v[62:65]
	v_mfma_f32_16x16x32_bf16 v[66:69], v[164:167], v[184:187], v[66:69]
	v_mfma_f32_16x16x32_bf16 v[70:73], v[168:171], v[184:187], v[70:73]
	v_mfma_f32_16x16x32_bf16 v[74:77], v[176:179], v[184:187], v[74:77]
	v_mfma_f32_16x16x32_bf16 v[78:81], v[180:183], v[184:187], v[78:81]
	v_mfma_f32_16x16x32_bf16 v[82:85], v[164:167], v[148:151], v[82:85]
	v_mfma_f32_16x16x32_bf16 v[86:89], v[168:171], v[148:151], v[86:89]
	v_mfma_f32_16x16x32_bf16 v[90:93], v[176:179], v[148:151], v[90:93]
	v_mfma_f32_16x16x32_bf16 v[94:97], v[180:183], v[148:151], v[94:97]
	s_setprio 0
	s_mov_b32 s6, 1
	s_and_b64 vcc, exec, s[4:5]
	s_mov_b64 s[4:5], 0
	s_cbranch_vccnz .LBB0_3106
.LBB0_3108:
	s_or_b64 exec, exec, s[10:11]
	s_andn2_b64 vcc, exec, s[8:9]
	s_cbranch_vccnz .LBB0_3110
	s_bitcmp1_b32 s14, 0
	s_cselect_b32 s0, 0x4800, 0
	v_add_u32_e32 v174, s0, v145
	v_add3_u32 v223, v174, v219, v220
	v_add3_u32 v174, v174, v221, v220
	s_waitcnt vmcnt(1)
	ds_write_b128 v223, v[102:105]
	s_waitcnt vmcnt(0)
	ds_write_b128 v174, v[98:101] offset:9216

.Lnsa_selx_3:
	v_mov_b32_e32 v139, v97
	v_mov_b32_e32 v138, v96
	v_mov_b32_e32 v141, v95
	v_mov_b32_e32 v140, v94
	v_mov_b32_e32 v143, v93
	v_mov_b32_e32 v142, v92
	v_mov_b32_e32 v149, v91
	v_mov_b32_e32 v148, v90
	v_mov_b32_e32 v151, v89
	v_mov_b32_e32 v150, v88
	v_mov_b32_e32 v153, v87
	v_mov_b32_e32 v152, v86
	v_mov_b32_e32 v155, v85
	v_mov_b32_e32 v154, v84
	v_mov_b32_e32 v157, v83
	v_mov_b32_e32 v156, v82
	v_mov_b32_e32 v159, v81
	v_mov_b32_e32 v158, v80
	v_mov_b32_e32 v161, v79
	v_mov_b32_e32 v160, v78
	v_mov_b32_e32 v163, v77
	v_mov_b32_e32 v162, v76
	v_mov_b32_e32 v165, v75
	v_mov_b32_e32 v164, v74
	v_mov_b32_e32 v167, v73
	v_mov_b32_e32 v166, v72
	v_mov_b32_e32 v169, v71
	v_mov_b32_e32 v168, v70
	v_mov_b32_e32 v171, v69
	v_mov_b32_e32 v170, v68
	v_mov_b32_e32 v173, v67
	v_mov_b32_e32 v172, v66
	v_mov_b32_e32 v193, v37
	v_mov_b32_e32 v192, v36
	v_mov_b32_e32 v195, v35
	v_mov_b32_e32 v194, v34
	v_mov_b32_e32 v197, v41
	v_mov_b32_e32 v196, v40
	v_mov_b32_e32 v199, v39
	v_mov_b32_e32 v198, v38
	v_mov_b32_e32 v201, v45
	v_mov_b32_e32 v200, v44
	v_mov_b32_e32 v203, v43
	v_mov_b32_e32 v202, v42
	v_mov_b32_e32 v205, v49
	v_mov_b32_e32 v204, v48
	v_mov_b32_e32 v207, v47
	v_mov_b32_e32 v206, v46
	v_mov_b32_e32 v177, v53
	v_mov_b32_e32 v176, v52
	v_mov_b32_e32 v179, v51
	v_mov_b32_e32 v178, v50
	v_mov_b32_e32 v181, v57
	v_mov_b32_e32 v180, v56
	v_mov_b32_e32 v183, v55
	v_mov_b32_e32 v182, v54
	v_mov_b32_e32 v185, v61
	v_mov_b32_e32 v184, v60
	v_mov_b32_e32 v187, v59
	v_mov_b32_e32 v186, v58
	v_mov_b32_e32 v189, v65
	v_mov_b32_e32 v188, v64
	v_mov_b32_e32 v191, v63
	v_mov_b32_e32 v190, v62
	s_branch .LBB0_3115
